# GU unit loop: next-unit tile index / pointer SALU chain moved from in front of the K-loop into the peeled first load segment
# speedup vs baseline: 1.0107x; 1.0027x over previous
; #define PG8_STAGE(bufoff, gbase, voff) do { _Pragma("unroll") for (int _i = 0; _i < 2; ++_i) \
;         __builtin_amdgcn_global_load_lds((const unsigned*)((const char*)(gbase) + (voff)[_i]), (PG8_LAS unsigned*)(lds + (bufoff) + ldsw + _i * 8192), 16, 0, 0); } while (0)
; #define PG8_LDA(dst, b, h) do { _Pragma("unroll") for (int m = 0; m < 4; ++m) _Pragma("unroll") for (int k = 0; k < 2; ++k) dst[m][k] = *(const PG8_LAS bf16x8*)(lds + PG8_SA(b, h) + aoff + m * 2048 + k * 1024); } while (0)
; #define PG8_LDB(dst, b, h) do { _Pragma("unroll") for (int n = 0; n < 2; ++n) _Pragma("unroll") for (int k = 0; k < 2; ++k) dst[n][k] = *(const PG8_LAS bf16x8*)(lds + PG8_SB(b, h) + boff + n * 2048 + k * 1024); } while (0)
; #define PG8_SCHED __builtin_amdgcn_sched_barrier(0)
;     __host__ __device__ bool next(int i, Unit& u) const {
;         const long L = (long)i * G + c; if (L >= nwg) return false;
;         int wgid = (int)L; { const int q = nwg / NXCD, r = nwg % NXCD, xcd = wgid % NXCD, off = wgid / NXCD; wgid = (xcd < r ? xcd * (q + 1) : r * (q + 1) + (xcd - r) * q) + off; }
;         const int nig = WGM * nN, gid = wgid / nig, fm = gid * WGM, gsz = (nM - fm) < WGM ? (nM - fm) : WGM;
;         u.pm = fm + ((wgid % nig) % gsz); u.pn = (wgid % nig) / gsz; u.k0 = 0; u.len = nt; u.kind = 0; return true;
; template <class Epi, class Sched, bool ALIGN_EPI = false, bool SP2 = false>
; __device__ __forceinline__ void gemm_phase(PG8_LAS unsigned char* lds, const Gemm g, const Sched& S, const Epi& E, const int wave_s) {
;     ...
;             PG8_LDB(B0, 0, 0); PG8_LDB(B1, 0, 1); PG8_SCHED; PG8_LDA(At, 0, 0); PG8_STAGE(PG8_SA(1, 1), a1 + hstep, voffA);
.LBB0_516:
	s_add_u32 s24, s24, 0x40080
	s_addc_u32 s25, s25, 0
	s_add_u32 s48, s2, 0x100
	s_addc_u32 s49, s3, 0
	s_mov_b32 s50, -2
	s_add_u32 s2, s24, 0xfffc0080
	s_addc_u32 s3, s25, -1
	s_add_i32 s51, 0, 0x10000
	s_cmp_eq_u32 s50, 12
	s_cselect_b32 s27, s19, s3
	s_cselect_b32 s26, s46, s2
	v_add_u32_e32 v144, s51, v147
	s_cselect_b32 s3, s17, s49
	s_cselect_b32 s2, s47, s48
	s_add_i32 s54, 0, 0x14000
	ds_read_b128 v[140:143], v144
	ds_read_b128 v[150:153], v144 offset:1024
	ds_read_b128 v[154:157], v144 offset:2048
	ds_read_b128 v[158:161], v144 offset:3072
	v_add_u32_e32 v144, s54, v147
	ds_read_b128 v[174:177], v144
	ds_read_b128 v[178:181], v144 offset:1024
	ds_read_b128 v[182:185], v144 offset:2048
	ds_read_b128 v[186:189], v144 offset:3072
	v_lshl_add_u64 v[194:195], s[24:25], 0, v[136:137]
	s_add_i32 m0, s35, 0xc000
	ds_read_b128 v[190:193], v148
	ds_read_b128 v[210:213], v148 offset:1024
	ds_read_b128 v[214:217], v148 offset:2048
	ds_read_b128 v[218:221], v148 offset:3072
	ds_read_b128 v[222:225], v148 offset:4096
	ds_read_b128 v[226:229], v148 offset:5120
	ds_read_b128 v[230:233], v148 offset:6144
	ds_read_b128 v[234:237], v148 offset:7168
	global_load_lds_dwordx4 v[194:195], off
	v_lshl_add_u64 v[194:195], s[24:25], 0, v[138:139]
	s_add_i32 m0, s35, 0xe000
	s_nop 0
	global_load_lds_dwordx4 v[194:195], off
	s_add_i32 s43, s43, 1
	s_mul_i32 s6, s43, s80
	s_mul_hi_u32 s7, s43, s93
	s_add_i32 s7, s7, s6
	s_mul_i32 s6, s43, s93
	s_add_u32 s20, s6, s64
	s_addc_u32 s21, s7, s65
	v_cmp_gt_i64_e32 vcc, s[20:21], v[168:169]
	v_cmp_lt_i64_e64 s[6:7], s[20:21], v[166:167]
	s_cbranch_vccnz .Lgum_522
	s_ashr_i32 s16, s20, 31
	s_lshr_b32 s16, s16, 29
	s_add_i32 s18, s20, s16
	s_and_b32 s16, s18, -8
	s_sub_i32 s19, s20, s16
	s_cmp_gt_i32 s19, 5
	s_mov_b64 s[16:17], -1
	s_cbranch_scc0 .Lgum_519
	s_mul_i32 s16, s19, 0xbd
	s_add_i32 s20, s16, 6
	s_mov_b64 s[16:17], 0

;     __host__ __device__ bool next(int i, Unit& u) const {
;     ...
;         int wgid = (int)L; { const int q = nwg / NXCD, r = nwg % NXCD, xcd = wgid % NXCD, off = wgid / NXCD; wgid = (xcd < r ? xcd * (q + 1) : r * (q + 1) + (xcd - r) * q) + off; }
;         const int nig = WGM * nN, gid = wgid / nig, fm = gid * WGM, gsz = (nM - fm) < WGM ? (nM - fm) : WGM;
;         u.pm = fm + ((wgid % nig) % gsz); u.pn = (wgid % nig) / gsz; u.k0 = 0; u.len = nt; u.kind = 0; return true;
.Lgum_521:
	s_ashr_i32 s16, s18, 3
	s_add_i32 s16, s20, s16
	s_mul_hi_i32 s17, s16, 0x2e8ba2e9
	s_lshr_b32 s18, s17, 31
	s_ashr_i32 s17, s17, 5
	s_add_i32 s17, s17, s18
	s_lshl_b32 s18, s17, 3
	s_sub_i32 s19, 0x45, s18
	s_min_i32 s19, s19, 8
	s_abs_i32 s20, s19
	v_cvt_f32_u32_e32 v246, s20
	s_sub_i32 s22, 0, s20
	s_mulk_i32 s17, 0xb0
	s_sub_i32 s17, s16, s17
	v_rcp_iflag_f32_e32 v246, v246
	s_abs_i32 s16, s17
	s_xor_b32 s21, s17, s19
	s_ashr_i32 s21, s21, 31
	v_mul_f32_e32 v246, 0x4f7ffffe, v246
	v_cvt_u32_f32_e32 v246, v246
	s_nop 0
	v_readfirstlane_b32 s23, v246
	s_mul_i32 s22, s22, s23
	s_mul_hi_u32 s22, s23, s22
	s_add_i32 s23, s23, s22
	s_mul_hi_u32 s22, s16, s23
	s_mul_i32 s23, s22, s20
	s_sub_i32 s16, s16, s23
	s_add_i32 s100, s22, 1
	s_sub_i32 s23, s16, s20
	s_cmp_ge_u32 s16, s20
	s_cselect_b32 s22, s100, s22
	s_cselect_b32 s16, s23, s16
	s_add_i32 s23, s22, 1
	s_cmp_ge_u32 s16, s20
	s_cselect_b32 s16, s23, s22
	s_xor_b32 s16, s16, s21
	s_sub_i32 s16, s16, s21
	s_mul_i32 s19, s16, s19
	s_sub_i32 s17, s17, s19
	s_add_i32 s18, s18, s17
; #define PG8_STAGE(bufoff, gbase, voff) do { _Pragma("unroll") for (int _i = 0; _i < 2; ++_i) \
;         __builtin_amdgcn_global_load_lds((const unsigned*)((const char*)(gbase) + (voff)[_i]), (PG8_LAS unsigned*)(lds + (bufoff) + ldsw + _i * 8192), 16, 0, 0); } while (0)
; #define PG8_LDA(dst, b, h) do { _Pragma("unroll") for (int m = 0; m < 4; ++m) _Pragma("unroll") for (int k = 0; k < 2; ++k) dst[m][k] = *(const PG8_LAS bf16x8*)(lds + PG8_SA(b, h) + aoff + m * 2048 + k * 1024); } while (0)
; #define PG8_LDB(dst, b, h) do { _Pragma("unroll") for (int n = 0; n < 2; ++n) _Pragma("unroll") for (int k = 0; k < 2; ++k) dst[n][k] = *(const PG8_LAS bf16x8*)(lds + PG8_SB(b, h) + boff + n * 2048 + k * 1024); } while (0)
; #define PG8_MMA(ai, bj, At, Bt) do { __builtin_amdgcn_s_setprio(1); _Pragma("unroll") for (int m = 0; m < 4; ++m) _Pragma("unroll") for (int n = 0; n < 2; ++n) _Pragma("unroll") for (int k = 0; k < 2; ++k) \
;         acc[ai][bj][m][n] = __builtin_amdgcn_mfma_f32_16x16x32_bf16(Bt[n][k], At[m][k], acc[ai][bj][m][n], 0, 0, 0); __builtin_amdgcn_s_setprio(0); } while (0)
; #define PG8_WAIT_V(n) asm volatile("s_waitcnt vmcnt(" #n ")" ::: "memory")
; #define PG8_WAIT_L(n) asm volatile("s_waitcnt lgkmcnt(" #n ")" ::: "memory")
; #define PG8_BAR __builtin_amdgcn_s_barrier()
; #define PG8_SCHED __builtin_amdgcn_sched_barrier(0)
; template <class Epi, class Sched, bool ALIGN_EPI = false, bool SP2 = false>
; __device__ __forceinline__ void gemm_phase(PG8_LAS unsigned char* lds, const Gemm g, const Sched& S, const Epi& E, const int wave_s) {
;     ...
;         const char* nA = has_next ? (const char*)g.A + (size_t)nxt.pm * tstep + (size_t)nxt.k0 * kstep : cA; const char* nB = has_next ? (const char*)g.Bt + (size_t)nxt.pn * tstep + (size_t)nxt.k0 * kstep : cB;
;     ...
;             PG8_LDB(B0, 0, 0); PG8_LDB(B1, 0, 1); PG8_SCHED; PG8_LDA(At, 0, 0); PG8_STAGE(PG8_SA(1, 1), a1 + hstep, voffA);
;             PG8_WAIT_V(8); PG8_WAIT_L(0); PG8_BAR; PG8_MMA(0, 0, At, B0); PG8_MMA(0, 1, At, B1); PG8_BAR; PG8_SCHED;
;             PG8_LDA(At, 0, 1); PG8_STAGE(PG8_SB(0, 0), b2, voffB); PG8_STAGE(PG8_SB(0, 1), b2 + hstep, voffB); PG8_STAGE(PG8_SA(0, 0), a2, voffA);
;             PG8_WAIT_V(8); PG8_WAIT_L(0); PG8_BAR; PG8_MMA(1, 0, At, B0); PG8_MMA(1, 1, At, B1); PG8_BAR; PG8_SCHED;
.Lgum_522:
	s_ashr_i32 s19, s18, 31
	s_lshl_b64 s[20:21], s[18:19], 19
	s_add_u32 s20, s28, s20
	s_addc_u32 s21, s29, s21
	s_and_b64 s[22:23], s[6:7], exec
	s_cselect_b32 s19, s21, s25
	s_cselect_b32 s46, s20, s24
	s_ashr_i32 s17, s16, 31
	s_lshl_b64 s[22:23], s[16:17], 19
	s_add_u32 s22, s30, s22
	s_addc_u32 s23, s31, s23
	s_and_b64 s[100:101], s[6:7], exec
	s_cselect_b32 s17, s23, s49
	s_cselect_b32 s47, s22, s48
	s_waitcnt vmcnt(8)
	s_waitcnt lgkmcnt(0)
	s_barrier
	s_setprio 1
	s_waitcnt lgkmcnt(0)
	v_mfma_f32_16x16x32_bf16 v[124:127], v[140:143], v[190:193], 0
	v_mfma_f32_16x16x32_bf16 v[116:119], v[154:157], v[190:193], 0
	v_mfma_f32_16x16x32_bf16 v[108:111], v[140:143], v[214:217], 0
	v_mfma_f32_16x16x32_bf16 v[100:103], v[154:157], v[214:217], 0
	v_mfma_f32_16x16x32_bf16 v[92:95], v[140:143], v[222:225], 0
	v_mfma_f32_16x16x32_bf16 v[84:87], v[154:157], v[222:225], 0
	v_mfma_f32_16x16x32_bf16 v[76:79], v[140:143], v[230:233], 0
	v_mfma_f32_16x16x32_bf16 v[68:71], v[154:157], v[230:233], 0
	v_mfma_f32_16x16x32_bf16 v[124:127], v[150:153], v[210:213], v[124:127]
	v_mfma_f32_16x16x32_bf16 v[116:119], v[158:161], v[210:213], v[116:119]
	v_mfma_f32_16x16x32_bf16 v[108:111], v[150:153], v[218:221], v[108:111]
	v_mfma_f32_16x16x32_bf16 v[100:103], v[158:161], v[218:221], v[100:103]
	v_mfma_f32_16x16x32_bf16 v[92:95], v[150:153], v[226:229], v[92:95]
	v_mfma_f32_16x16x32_bf16 v[84:87], v[158:161], v[226:229], v[84:87]
	v_mfma_f32_16x16x32_bf16 v[76:79], v[150:153], v[234:237], v[76:79]
	v_mfma_f32_16x16x32_bf16 v[68:71], v[158:161], v[234:237], v[68:71]
	s_setprio 0
	s_setprio 1
	v_mfma_f32_16x16x32_bf16 v[120:123], v[174:177], v[190:193], 0
	v_mfma_f32_16x16x32_bf16 v[112:115], v[182:185], v[190:193], 0
	v_mfma_f32_16x16x32_bf16 v[104:107], v[174:177], v[214:217], 0
	v_mfma_f32_16x16x32_bf16 v[96:99], v[182:185], v[214:217], 0
	v_mfma_f32_16x16x32_bf16 v[88:91], v[174:177], v[222:225], 0
	v_mfma_f32_16x16x32_bf16 v[80:83], v[182:185], v[222:225], 0
	v_mfma_f32_16x16x32_bf16 v[72:75], v[174:177], v[230:233], 0
	v_mfma_f32_16x16x32_bf16 v[64:67], v[182:185], v[230:233], 0
	v_mfma_f32_16x16x32_bf16 v[120:123], v[178:181], v[210:213], v[120:123]
	v_mfma_f32_16x16x32_bf16 v[112:115], v[186:189], v[210:213], v[112:115]
	v_mfma_f32_16x16x32_bf16 v[104:107], v[178:181], v[218:221], v[104:107]
	v_mfma_f32_16x16x32_bf16 v[96:99], v[186:189], v[218:221], v[96:99]
	v_mfma_f32_16x16x32_bf16 v[88:91], v[178:181], v[226:229], v[88:91]
	v_mfma_f32_16x16x32_bf16 v[80:83], v[186:189], v[226:229], v[80:83]
	v_mfma_f32_16x16x32_bf16 v[72:75], v[178:181], v[234:237], v[72:75]
	v_mfma_f32_16x16x32_bf16 v[64:67], v[186:189], v[234:237], v[64:67]
	s_setprio 0
	s_barrier
	s_add_i32 s51, s51, s34
	v_lshl_add_u64 v[194:195], s[2:3], 0, v[128:129]
	s_mov_b32 m0, s51
	ds_read_b128 v[190:193], v148 offset:16384
	ds_read_b128 v[210:213], v148 offset:17408
	ds_read_b128 v[214:217], v148 offset:18432
	ds_read_b128 v[218:221], v148 offset:19456
	ds_read_b128 v[222:225], v148 offset:20480
	ds_read_b128 v[226:229], v148 offset:21504
	ds_read_b128 v[230:233], v148 offset:22528
	ds_read_b128 v[234:237], v148 offset:23552
	global_load_lds_dwordx4 v[194:195], off
	s_add_i32 m0, s51, 0x2000
	s_add_u32 s52, s2, 0x40000
	v_lshl_add_u64 v[238:239], s[2:3], 0, v[130:131]
	s_addc_u32 s53, s3, 0
	s_add_i32 s51, s54, s34
	global_load_lds_dwordx4 v[238:239], off
	v_lshl_add_u64 v[240:241], s[52:53], 0, v[128:129]
	s_mov_b32 m0, s51
	v_lshl_add_u64 v[242:243], s[26:27], 0, v[132:133]
	global_load_lds_dwordx4 v[240:241], off
	v_lshl_add_u64 v[240:241], s[52:53], 0, v[130:131]
	s_add_i32 m0, s51, 0x2000
	s_nop 0
	global_load_lds_dwordx4 v[240:241], off
	v_lshl_add_u64 v[240:241], s[26:27], 0, v[134:135]
	s_mov_b32 m0, s35
	s_nop 0
	global_load_lds_dwordx4 v[240:241], off
	s_mov_b32 m0, s36
	s_nop 0
	global_load_lds_dwordx4 v[242:243], off
	s_waitcnt vmcnt(8)
	s_waitcnt lgkmcnt(0)
	s_barrier
	s_setprio 1
	s_waitcnt lgkmcnt(0)
	v_mfma_f32_16x16x32_bf16 v[60:63], v[140:143], v[190:193], 0
	v_mfma_f32_16x16x32_bf16 v[52:55], v[154:157], v[190:193], 0
	v_mfma_f32_16x16x32_bf16 v[44:47], v[140:143], v[214:217], 0
	v_mfma_f32_16x16x32_bf16 v[36:39], v[154:157], v[214:217], 0
	v_mfma_f32_16x16x32_bf16 v[28:31], v[140:143], v[222:225], 0
	v_mfma_f32_16x16x32_bf16 v[20:23], v[154:157], v[222:225], 0
	v_mfma_f32_16x16x32_bf16 v[12:15], v[140:143], v[230:233], 0
	v_mfma_f32_16x16x32_bf16 v[4:7], v[154:157], v[230:233], 0
	v_mfma_f32_16x16x32_bf16 v[60:63], v[150:153], v[210:213], v[60:63]
	v_mfma_f32_16x16x32_bf16 v[52:55], v[158:161], v[210:213], v[52:55]
	v_mfma_f32_16x16x32_bf16 v[44:47], v[150:153], v[218:221], v[44:47]
	v_mfma_f32_16x16x32_bf16 v[36:39], v[158:161], v[218:221], v[36:39]
	v_mfma_f32_16x16x32_bf16 v[28:31], v[150:153], v[226:229], v[28:31]
	v_mfma_f32_16x16x32_bf16 v[20:23], v[158:161], v[226:229], v[20:23]
	v_mfma_f32_16x16x32_bf16 v[12:15], v[150:153], v[234:237], v[12:15]
	v_mfma_f32_16x16x32_bf16 v[4:7], v[158:161], v[234:237], v[4:7]
	s_setprio 0
	s_setprio 1
	v_mfma_f32_16x16x32_bf16 v[56:59], v[174:177], v[190:193], 0
	v_mfma_f32_16x16x32_bf16 v[48:51], v[182:185], v[190:193], 0
	v_mfma_f32_16x16x32_bf16 v[40:43], v[174:177], v[214:217], 0
	v_mfma_f32_16x16x32_bf16 v[32:35], v[182:185], v[214:217], 0
	v_mfma_f32_16x16x32_bf16 v[24:27], v[174:177], v[222:225], 0
	v_mfma_f32_16x16x32_bf16 v[16:19], v[182:185], v[222:225], 0
	v_mfma_f32_16x16x32_bf16 v[8:11], v[174:177], v[230:233], 0
	v_mfma_f32_16x16x32_bf16 v[0:3], v[182:185], v[230:233], 0
	v_mfma_f32_16x16x32_bf16 v[56:59], v[178:181], v[210:213], v[56:59]
	v_mfma_f32_16x16x32_bf16 v[48:51], v[186:189], v[210:213], v[48:51]
	v_mfma_f32_16x16x32_bf16 v[40:43], v[178:181], v[218:221], v[40:43]
	v_mfma_f32_16x16x32_bf16 v[32:35], v[186:189], v[218:221], v[32:35]
	v_mfma_f32_16x16x32_bf16 v[24:27], v[178:181], v[226:229], v[24:27]
	v_mfma_f32_16x16x32_bf16 v[16:19], v[186:189], v[226:229], v[16:19]
	v_mfma_f32_16x16x32_bf16 v[8:11], v[178:181], v[234:237], v[8:11]
	v_mfma_f32_16x16x32_bf16 v[0:3], v[186:189], v[234:237], v[0:3]
	s_setprio 0
	s_barrier
	s_branch .Lpeel1_seg3
